# gather phase: one static priority raise (s_setprio 1) for the role-1 block of each co-resident pair
# baseline (speedup 1.0000x reference)
.LBB0_1058:
	s_or_b64 exec, exec, s[0:1]
	s_waitcnt lgkmcnt(0)
	s_barrier
	s_and_saveexec_b64 s[0:1], s[52:53]
	s_cbranch_execz .LBB0_1067
	v_readlane_b32 s22, v246, 26
	s_nop 3
	s_cmp_lg_u32 s22, 0
	s_cbranch_scc0 .Lp10_noprio
	s_setprio 1
.Lp10_noprio:
	v_and_b32_e32 v2, 8, v130
	v_cmp_eq_u32_e64 s[0:1], 0, v2
	v_and_b32_e32 v2, 4, v130
	v_readlane_b32 s12, v247, 2
	v_cmp_eq_u32_e64 s[2:3], 0, v2
	v_and_b32_e32 v2, 2, v130
	v_readlane_b32 s13, v247, 3
	v_readlane_b32 s15, v247, 5
	v_cmp_eq_u32_e64 s[4:5], 0, v2
	v_and_b32_e32 v2, 1, v130
	v_cmp_lt_i32_e32 vcc, v81, v83
	v_readlane_b32 s16, v247, 6
	s_and_b32 s13, s13, 0xffff
	s_and_b32 s15, s15, 0xffff
	v_mov_b32_e32 v77, 0
	v_cmp_eq_u32_e64 s[6:7], 0, v2
	v_cndmask_b32_e32 v2, v75, v81, vcc
	v_cmp_lt_i32_e32 vcc, v154, v83
	v_readlane_b32 s36, v247, 61
	s_mov_b32 s11, 0x20000
	s_mov_b32 s10, 0x800000
	v_readlane_b32 s14, v247, 4
	v_readlane_b32 s17, v247, 7
	v_readlane_b32 s18, v247, 8
	v_readlane_b32 s19, v247, 9
	s_add_u32 s16, s74, 0x1000000
	v_lshlrev_b32_e32 v0, 1, v74
	v_mov_b32_e32 v1, v77
	v_lshlrev_b32_e32 v73, 2, v2
	v_cndmask_b32_e32 v2, v75, v154, vcc
	v_readlane_b32 s44, v248, 5
	v_readlane_b32 s45, v248, 6
	s_addc_u32 s17, s75, 0
	v_lshl_add_u64 v[0:1], s[68:69], 0, v[0:1]
	v_lshlrev_b32_e32 v82, 2, v2
	v_lshl_add_u64 v[2:3], s[44:45], 0, v[76:77]
	v_or_b32_e32 v83, v79, v137
	s_mov_b64 s[18:19], 0
	s_mov_b32 s8, s12
	s_mov_b32 s9, s13
	s_mov_b32 s12, s14
	s_mov_b32 s13, s15
	s_mov_b32 s14, s10
	s_mov_b32 s15, s11
	s_mov_b32 s24, 0x378e98ab
	s_mov_b32 s25, 0x3b7cd369
	s_mov_b32 s26, 0xbcc618b2
	s_mov_b32 s27, 0x3dda74e4
	s_mov_b32 s28, 0x3f228afd
	s_mov_b32 s29, 0x3e03c728
	s_mov_b32 s30, 0xbfb8aa3b
	s_mov_b32 s31, 0x42ce8ed0
	s_mov_b32 s33, 0xc2b17218
	v_mov_b32_e32 v84, 0x3ba10414
	s_brev_b32 s34, -2
	s_mov_b64 s[20:21], 0x5000
	s_movk_i32 s35, 0x5000
	s_movk_i32 s36, 0x7fff
	v_mov_b32_e32 v85, 0xb9c68948
	v_mov_b32_e32 v86, 0x7f800000
	v_readlane_b32 s37, v247, 62
	v_readlane_b32 s38, v247, 63
	v_readlane_b32 s39, v248, 0
	v_readlane_b32 s40, v248, 1
	v_readlane_b32 s41, v248, 2
	v_readlane_b32 s42, v248, 3
	v_readlane_b32 s43, v248, 4
	v_readlane_b32 s46, v248, 7
	v_readlane_b32 s47, v248, 8
	v_readlane_b32 s48, v248, 9
	v_readlane_b32 s49, v248, 10
	v_readlane_b32 s50, v248, 11
	v_readlane_b32 s51, v248, 12
	v_min_i32_e32 v176, 0x7fff, v132
	v_ashrrev_i32_e32 v177, 31, v176
	v_lshlrev_b64 v[178:179], 9, v[176:177]
	v_lshl_or_b32 v178, v128, 2, v178
	v_lshl_add_u64 v[180:181], s[74:75], 0, v[178:179]
	global_load_dword v160, v[180:181], off
	global_load_dword v162, v[180:181], off offset:256
	v_lshlrev_b64 v[180:181], 11, v[176:177]
	v_lshl_add_u64 v[180:181], v[0:1], 0, v[180:181]
	global_load_dwordx4 v[164:167], v[180:181], off
	global_load_dwordx4 v[168:171], v[180:181], off offset:16
	v_lshl_add_u64 v[180:181], s[16:17], 0, v[178:179]
	v_or_b32_e32 v178, 0x100, v178
	v_lshl_add_u64 v[178:179], s[16:17], 0, v[178:179]
	global_load_dword v172, v[180:181], off
	global_load_dword v173, v[178:179], off
	s_waitcnt vmcnt(0)
	v_ashrrev_i32_e32 v161, 31, v160
	v_ashrrev_i32_e32 v163, 31, v162
	v_lshlrev_b64 v[176:177], 2, v[160:161]
	v_lshlrev_b64 v[178:179], 2, v[162:163]
	v_lshl_add_u64 v[180:181], s[54:55], 0, v[176:177]
	v_lshl_add_u64 v[176:177], s[56:57], 0, v[176:177]
	v_lshl_add_u64 v[182:183], s[54:55], 0, v[178:179]
	v_lshl_add_u64 v[178:179], s[56:57], 0, v[178:179]
	global_load_dword v174, v[176:177], off
	global_load_dword v175, v[178:179], off
	global_load_dword v161, v[180:181], off
	global_load_dword v163, v[182:183], off
	s_waitcnt vmcnt(0)
	s_branch .LBB0_1061
